# GU: leading half's epilogue-alignment barrier moved from the epilogue start to after its row-statistics math, so that part overlaps the trailing half's last MFMA block
# baseline (speedup 1.0000x reference)
; #define PG8_BAR __builtin_amdgcn_s_barrier()
; __device__ __forceinline__ float ssq_rs(ssq_t v) { return __builtin_amdgcn_rsqf((float)v * (1.0f / (16777216.0f * 1024.0f)) + RMS_EPS); }
;     __device__ __forceinline__ void operator()(const f32x4 (&acc)[2][2][4][2], const Unit& u, int wr, int wc, int fr, int fq) const {
;         const int row0 = u.pm * BM + wr * 64 + fr, col0 = u.pn * HALF + wc * 32 + 8 * fq;
;         float rsv[2][4]; ssq_t sv[2][4];
; #pragma unroll
;         for (int ai = 0; ai < 2; ++ai)
; #pragma unroll
;             for (int m = 0; m < 4; ++m) sv[ai][m] = ssq[row0 + ai * HALF + m * 16];
; #pragma unroll
;         for (int ai = 0; ai < 2; ++ai)
; #pragma unroll
;             for (int m = 0; m < 4; ++m) rsv[ai][m] = ssq_rs(sv[ai][m]);
; template <class Epi, class Sched, bool ALIGN_EPI = false, bool SP2 = true>
; __device__ __forceinline__ void gemm_phase(PG8_LAS unsigned char* lds, const Gemm g, const Sched& S, const Epi& E) {
;     ...
;         if constexpr (ALIGN_EPI) { if (wr == 0) PG8_BAR; }
.LBB0_131:
	v_add_u32_e32 v141, 0x14000, v147
	ds_read_b128 v[168:171], v141
	ds_read_b128 v[172:175], v141 offset:1024
	ds_read_b128 v[176:179], v141 offset:2048
	ds_read_b128 v[180:183], v141 offset:3072
	ds_read_b128 v[184:187], v150
	ds_read_b128 v[188:191], v150 offset:1024
	ds_read_b128 v[200:203], v150 offset:2048
	ds_read_b128 v[204:207], v150 offset:3072
	ds_read_b128 v[208:211], v150 offset:4096
	ds_read_b128 v[212:215], v150 offset:5120
	ds_read_b128 v[216:219], v150 offset:6144
	ds_read_b128 v[220:223], v150 offset:7168
	v_pk_mul_f32 v[126:127], v[122:123], v[126:127]
	v_pk_mul_f32 v[118:119], v[114:115], v[118:119]
	s_lshl_b32 s6, s16, 7
	s_or_b32 s6, s6, s35
	s_ashr_i32 s6, s6, 6
	s_mul_i32 s7, s58, 44
	s_add_i32 s6, s6, s7
	s_ashr_i32 s7, s6, 31
	s_lshl_b64 s[6:7], s[6:7], 15
	s_add_u32 s46, s62, s6
	s_addc_u32 s47, s63, s7
	v_pk_mul_f32 v[104:105], v[108:109], v[104:105]
	v_pk_mul_f32 v[106:107], v[110:111], v[106:107]
	v_pk_mul_f32 v[102:103], v[98:99], v[102:103]
	v_pk_mul_f32 v[88:89], v[92:93], v[88:89]
	v_pk_mul_f32 v[90:91], v[94:95], v[90:91]
	v_pk_mul_f32 v[86:87], v[82:83], v[86:87]
	v_pk_mul_f32 v[72:73], v[76:77], v[72:73]
	v_pk_mul_f32 v[74:75], v[78:79], v[74:75]
	v_pk_mul_f32 v[70:71], v[66:67], v[70:71]
	v_pk_mul_f32 v[56:57], v[60:61], v[56:57]
	v_pk_mul_f32 v[58:59], v[62:63], v[58:59]
	v_pk_mul_f32 v[54:55], v[50:51], v[54:55]
	v_pk_mul_f32 v[40:41], v[44:45], v[40:41]
	v_pk_mul_f32 v[42:43], v[46:47], v[42:43]
	v_pk_mul_f32 v[38:39], v[34:35], v[38:39]
	v_pk_mul_f32 v[24:25], v[28:29], v[24:25]
	v_pk_mul_f32 v[26:27], v[30:31], v[26:27]
	v_pk_mul_f32 v[22:23], v[18:19], v[22:23]
	v_pk_mul_f32 v[8:9], v[12:13], v[8:9]
	v_pk_mul_f32 v[10:11], v[14:15], v[10:11]
	v_pk_mul_f32 v[0:1], v[4:5], v[0:1]
	v_pk_mul_f32 v[2:3], v[6:7], v[2:3]
	s_waitcnt vmcnt(6)
	v_mov_b32_e32 v152, v238
	v_mov_b32_e32 v153, v239
	v_mov_b32_e32 v154, v240
	v_mov_b32_e32 v155, v241
	v_mov_b32_e32 v158, v242
	v_mov_b32_e32 v159, v243
	v_mov_b32_e32 v160, v244
	v_mov_b32_e32 v161, v245
	v_mov_b32_e32 v162, v246
	v_mov_b32_e32 v163, v247
	v_mov_b32_e32 v164, v248
	v_mov_b32_e32 v165, v249
	v_mov_b32_e32 v166, v250
	v_mov_b32_e32 v167, v251
	v_mov_b32_e32 v148, v228
	v_mov_b32_e32 v149, v229
	v_ffbh_u32_e32 v141, v153
	v_min_u32_e32 v141, 32, v141
	v_lshlrev_b64 v[152:153], v141, v[152:153]
	v_min_u32_e32 v143, 1, v152
	v_or_b32_e32 v143, v153, v143
	v_cvt_f32_u32_e32 v143, v143
	v_sub_u32_e32 v141, 32, v141
	v_ldexp_f32 v141, v143, v141
	v_ffbh_u32_e32 v143, v155
	v_min_u32_e32 v143, 32, v143
	v_lshlrev_b64 v[152:153], v143, v[154:155]
	v_min_u32_e32 v144, 1, v152
	v_or_b32_e32 v144, v153, v144
	v_cvt_f32_u32_e32 v144, v144
	v_sub_u32_e32 v143, 32, v143
	v_fmamk_f32 v141, v141, 0x2e800000, v193
	v_rsq_f32_e32 v141, v141
	v_ldexp_f32 v143, v144, v143
	v_fmamk_f32 v143, v143, 0x2e800000, v193
	v_rsq_f32_e32 v156, v143
	v_ffbh_u32_e32 v143, v159
	v_min_u32_e32 v143, 32, v143
	v_lshlrev_b64 v[152:153], v143, v[158:159]
	v_min_u32_e32 v144, 1, v152
	v_or_b32_e32 v144, v153, v144
	v_cvt_f32_u32_e32 v144, v144
	v_sub_u32_e32 v143, 32, v143
	v_ldexp_f32 v143, v144, v143
	v_fmamk_f32 v143, v143, 0x2e800000, v193
	v_rsq_f32_e32 v155, v143
	v_ffbh_u32_e32 v143, v161
	v_min_u32_e32 v143, 32, v143
	v_lshlrev_b64 v[152:153], v143, v[160:161]
	v_min_u32_e32 v144, 1, v152
	v_or_b32_e32 v144, v153, v144
	v_cvt_f32_u32_e32 v144, v144
	v_sub_u32_e32 v143, 32, v143
	v_ldexp_f32 v143, v144, v143
	v_fmamk_f32 v143, v143, 0x2e800000, v193
	v_rsq_f32_e32 v154, v143
	v_ffbh_u32_e32 v143, v163
	v_min_u32_e32 v143, 32, v143
	v_lshlrev_b64 v[152:153], v143, v[162:163]
	v_min_u32_e32 v144, 1, v152
	v_or_b32_e32 v144, v153, v144
	v_cvt_f32_u32_e32 v144, v144
	v_sub_u32_e32 v143, 32, v143
	v_ldexp_f32 v143, v144, v143
	v_ffbh_u32_e32 v144, v165
	v_min_u32_e32 v144, 32, v144
	v_lshlrev_b64 v[152:153], v144, v[164:165]
	v_min_u32_e32 v146, 1, v152
	v_or_b32_e32 v146, v153, v146
	v_cvt_f32_u32_e32 v146, v146
	v_sub_u32_e32 v144, 32, v144
	v_fmamk_f32 v143, v143, 0x2e800000, v193
	v_rsq_f32_e32 v143, v143
	v_ldexp_f32 v144, v146, v144
	v_fmamk_f32 v144, v144, 0x2e800000, v193
	v_rsq_f32_e32 v153, v144
	v_ffbh_u32_e32 v144, v167
	v_min_u32_e32 v144, 32, v144
	v_lshlrev_b64 v[158:159], v144, v[166:167]
	v_min_u32_e32 v146, 1, v158
	v_or_b32_e32 v146, v159, v146
	v_cvt_f32_u32_e32 v146, v146
	v_sub_u32_e32 v144, 32, v144
	v_ldexp_f32 v144, v146, v144
	v_fmamk_f32 v144, v144, 0x2e800000, v193
	v_rsq_f32_e32 v152, v144
	v_ffbh_u32_e32 v144, v149
	v_min_u32_e32 v144, 32, v144
	v_lshlrev_b64 v[148:149], v144, v[148:149]
	v_min_u32_e32 v146, 1, v148
	v_or_b32_e32 v146, v149, v146
	v_cvt_f32_u32_e32 v146, v146
	v_sub_u32_e32 v144, 32, v144
	v_ldexp_f32 v144, v146, v144
	s_cmp_lg_u64 s[20:21], 0
	s_cbranch_scc0 .Lgu_no_align
	s_barrier
; __device__ __forceinline__ unsigned cvt_pk_bf16(float lo, float hi) { unsigned r; asm volatile("v_cvt_pk_bf16_f32 %0, %1, %2" : "=v"(r) : "v"(lo), "v"(hi)); return r; }
;     __device__ __forceinline__ void operator()(const f32x4 (&acc)[2][2][4][2], const Unit& u, int wr, int wc, int fr, int fq) const {
;     ...
;             for (int m = 0; m < 4; ++m) {
;                 const int row = row0 + ai * HALF + m * 16;
;                 const float rs = rsv[ai][m], nrs = rs * -1.44269504089f, rs2 = rs * rs;
;                 typedef float f32x2 __attribute__((ext_vector_type(2)));
;                 float a[8];
; #pragma unroll
;                 for (int n = 0; n < 2; ++n)
; #pragma unroll
;                     for (int hf = 0; hf < 2; ++hf) {
;                         const f32x2 g2 = (f32x2){acc[ai][0][m][n][2 * hf], acc[ai][0][m][n][2 * hf + 1]}, u2 = (f32x2){acc[ai][1][m][n][2 * hf], acc[ai][1][m][n][2 * hf + 1]};
;                         const f32x2 t = g2 * nrs;
;                         f32x2 e; e.x = __builtin_amdgcn_exp2f(t.x); e.y = __builtin_amdgcn_exp2f(t.y);
;                         const f32x2 d = e + 1.0f;
;                         f32x2 r; r.x = __builtin_amdgcn_rcpf(d.x); r.y = __builtin_amdgcn_rcpf(d.y);
;                         const f32x2 o = (g2 * u2) * (r * rs2);
;                         a[n * 4 + 2 * hf] = o.x; a[n * 4 + 2 * hf + 1] = o.y;
;                     }
;                 u32x4 w; w.x = cvt_pk_bf16(a[0], a[1]); w.y = cvt_pk_bf16(a[2], a[3]); w.z = cvt_pk_bf16(a[4], a[5]); w.w = cvt_pk_bf16(a[6], a[7]);
;                 __builtin_nontemporal_store(w, (u32x4*)(O + ((size_t)(u.pm * (ldc >> 6) + (col0 >> 6)) * 256 + (row & 255)) * 64 + (col0 & 63)));
.Lgu_no_align:
	v_mul_f32_e32 v146, 0xbfb8aa3b, v141
	v_pk_mul_f32 v[148:149], v[120:121], v[146:147] op_sel_hi:[1,0]
	v_fmamk_f32 v144, v144, 0x2e800000, v193
	v_exp_f32_e32 v148, v148
	v_exp_f32_e32 v149, v149
	v_rsq_f32_e32 v151, v144
	v_mul_f32_e32 v144, v141, v141
	v_pk_mul_f32 v[120:121], v[120:121], v[124:125]
	v_pk_add_f32 v[148:149], v[148:149], 1.0 op_sel_hi:[1,0]
	v_pk_mul_f32 v[122:123], v[122:123], v[146:147] op_sel_hi:[1,0]
	v_rcp_f32_e32 v148, v148
	v_rcp_f32_e32 v149, v149
	v_pk_mul_f32 v[114:115], v[114:115], v[146:147] op_sel_hi:[1,0]
	v_exp_f32_e32 v122, v122
	v_exp_f32_e32 v123, v123
	v_pk_mul_f32 v[124:125], v[144:145], v[148:149] op_sel_hi:[0,1]
	v_pk_mul_f32 v[120:121], v[120:121], v[124:125]
	v_pk_mul_f32 v[124:125], v[112:113], v[146:147] op_sel_hi:[1,0]
	v_exp_f32_e32 v114, v114
	v_exp_f32_e32 v124, v124
	v_exp_f32_e32 v125, v125
	v_exp_f32_e32 v115, v115
	v_pk_add_f32 v[122:123], v[122:123], 1.0 op_sel_hi:[1,0]
	v_pk_mul_f32 v[112:113], v[112:113], v[116:117]
	v_pk_add_f32 v[124:125], v[124:125], 1.0 op_sel_hi:[1,0]
	v_pk_add_f32 v[114:115], v[114:115], 1.0 op_sel_hi:[1,0]
	v_rcp_f32_e32 v124, v124
	v_rcp_f32_e32 v125, v125
	v_rcp_f32_e32 v122, v122
	v_rcp_f32_e32 v123, v123
	v_rcp_f32_e32 v114, v114
	v_rcp_f32_e32 v115, v115
	v_pk_mul_f32 v[116:117], v[144:145], v[124:125] op_sel_hi:[0,1]
	v_pk_mul_f32 v[122:123], v[144:145], v[122:123] op_sel_hi:[0,1]
	v_pk_mul_f32 v[112:113], v[112:113], v[116:117]
	v_pk_mul_f32 v[114:115], v[144:145], v[114:115] op_sel_hi:[0,1]
	v_pk_mul_f32 v[122:123], v[126:127], v[122:123]
	v_pk_mul_f32 v[118:119], v[118:119], v[114:115]
	v_cvt_pk_bf16_f32 v114, v120, v121
	v_cvt_pk_bf16_f32 v115, v122, v123
	v_cvt_pk_bf16_f32 v116, v112, v113
	v_lshl_add_u64 v[112:113], s[46:47], 0, v[194:195]
	v_mov_b32_e32 v141, v195
	v_lshl_add_u64 v[112:113], v[112:113], 0, v[140:141]
	v_cvt_pk_bf16_f32 v117, v118, v119
	global_store_dwordx4 v[112:113], v[114:117], off nt
	s_nop 1
	v_mul_f32_e32 v114, 0xbfb8aa3b, v156
	v_pk_mul_f32 v[118:119], v[108:109], v[114:115] op_sel_hi:[1,0]
	v_mul_f32_e32 v116, v156, v156
	v_exp_f32_e32 v118, v118
	v_exp_f32_e32 v119, v119
	s_nop 0
	v_pk_add_f32 v[118:119], v[118:119], 1.0 op_sel_hi:[1,0]
	s_nop 0
	v_rcp_f32_e32 v118, v118
	v_rcp_f32_e32 v119, v119
	s_nop 0
	v_pk_mul_f32 v[108:109], v[116:117], v[118:119] op_sel_hi:[0,1]
	v_pk_mul_f32 v[104:105], v[104:105], v[108:109]
	v_pk_mul_f32 v[108:109], v[110:111], v[114:115] op_sel_hi:[1,0]
	s_nop 0
	v_exp_f32_e32 v108, v108
	v_exp_f32_e32 v109, v109
	s_nop 0
	v_pk_add_f32 v[108:109], v[108:109], 1.0 op_sel_hi:[1,0]
	s_nop 0
	v_rcp_f32_e32 v108, v108
	v_rcp_f32_e32 v109, v109
	s_nop 0
	v_pk_mul_f32 v[108:109], v[116:117], v[108:109] op_sel_hi:[0,1]
	v_pk_mul_f32 v[106:107], v[106:107], v[108:109]
	v_pk_mul_f32 v[108:109], v[96:97], v[114:115] op_sel_hi:[1,0]
	v_pk_mul_f32 v[96:97], v[96:97], v[100:101]
	v_exp_f32_e32 v108, v108
	v_exp_f32_e32 v109, v109
	s_nop 0
	v_pk_add_f32 v[108:109], v[108:109], 1.0 op_sel_hi:[1,0]
	s_nop 0
	v_rcp_f32_e32 v108, v108
	v_rcp_f32_e32 v109, v109
	s_nop 0
	v_pk_mul_f32 v[100:101], v[116:117], v[108:109] op_sel_hi:[0,1]
	v_pk_mul_f32 v[100:101], v[96:97], v[100:101]
	v_pk_mul_f32 v[96:97], v[98:99], v[114:115] op_sel_hi:[1,0]
	s_nop 0
	v_exp_f32_e32 v96, v96
	v_exp_f32_e32 v97, v97
	s_nop 0
	v_pk_add_f32 v[96:97], v[96:97], 1.0 op_sel_hi:[1,0]
	s_nop 0
	v_rcp_f32_e32 v96, v96
	v_rcp_f32_e32 v97, v97
	s_nop 0
	v_pk_mul_f32 v[96:97], v[116:117], v[96:97] op_sel_hi:[0,1]
	v_pk_mul_f32 v[102:103], v[102:103], v[96:97]
	v_cvt_pk_bf16_f32 v96, v104, v105
	v_cvt_pk_bf16_f32 v97, v106, v107
	v_cvt_pk_bf16_f32 v98, v100, v101
	s_nop 0
	v_cvt_pk_bf16_f32 v99, v102, v103
	global_store_dwordx4 v[112:113], v[96:99], off offset:2048 nt
	s_nop 1
	v_mul_f32_e32 v96, 0xbfb8aa3b, v155
	v_pk_mul_f32 v[100:101], v[92:93], v[96:97] op_sel_hi:[1,0]
	v_mul_f32_e32 v98, v155, v155
	v_exp_f32_e32 v100, v100
	v_exp_f32_e32 v101, v101
	s_nop 0
	v_pk_add_f32 v[100:101], v[100:101], 1.0 op_sel_hi:[1,0]
	s_nop 0
	v_rcp_f32_e32 v100, v100
	v_rcp_f32_e32 v101, v101
	s_nop 0
	v_pk_mul_f32 v[92:93], v[98:99], v[100:101] op_sel_hi:[0,1]
	v_pk_mul_f32 v[88:89], v[88:89], v[92:93]
	v_pk_mul_f32 v[92:93], v[94:95], v[96:97] op_sel_hi:[1,0]
	s_nop 0
	v_exp_f32_e32 v92, v92
	v_exp_f32_e32 v93, v93
	s_nop 0
	v_pk_add_f32 v[92:93], v[92:93], 1.0 op_sel_hi:[1,0]
	s_nop 0
	v_rcp_f32_e32 v92, v92
	v_rcp_f32_e32 v93, v93
	s_nop 0
	v_pk_mul_f32 v[92:93], v[98:99], v[92:93] op_sel_hi:[0,1]
	v_pk_mul_f32 v[90:91], v[90:91], v[92:93]
	v_pk_mul_f32 v[92:93], v[80:81], v[96:97] op_sel_hi:[1,0]
	v_pk_mul_f32 v[80:81], v[80:81], v[84:85]
	v_exp_f32_e32 v92, v92
	v_exp_f32_e32 v93, v93
	s_nop 0
	v_pk_add_f32 v[92:93], v[92:93], 1.0 op_sel_hi:[1,0]
	s_nop 0
	v_rcp_f32_e32 v92, v92
	v_rcp_f32_e32 v93, v93
	s_nop 0
	v_pk_mul_f32 v[84:85], v[98:99], v[92:93] op_sel_hi:[0,1]
	v_pk_mul_f32 v[84:85], v[80:81], v[84:85]
	v_pk_mul_f32 v[80:81], v[82:83], v[96:97] op_sel_hi:[1,0]
	s_nop 0
	v_exp_f32_e32 v80, v80
	v_exp_f32_e32 v81, v81
	s_nop 0
	v_pk_add_f32 v[80:81], v[80:81], 1.0 op_sel_hi:[1,0]
	s_nop 0
	v_rcp_f32_e32 v80, v80
	v_rcp_f32_e32 v81, v81
	s_nop 0
	v_pk_mul_f32 v[80:81], v[98:99], v[80:81] op_sel_hi:[0,1]
	v_pk_mul_f32 v[86:87], v[86:87], v[80:81]
	v_cvt_pk_bf16_f32 v80, v88, v89
	v_cvt_pk_bf16_f32 v81, v90, v91
	v_cvt_pk_bf16_f32 v82, v84, v85
	v_add_co_u32_e32 v84, vcc, s23, v112
	v_cvt_pk_bf16_f32 v83, v86, v87
	s_nop 1
	v_addc_co_u32_e32 v85, vcc, 0, v113, vcc
	global_store_dwordx4 v[84:85], v[80:83], off nt
	s_nop 1
	v_mul_f32_e32 v80, 0xbfb8aa3b, v154
	v_pk_mul_f32 v[86:87], v[76:77], v[80:81] op_sel_hi:[1,0]
; __device__ __forceinline__ unsigned cvt_pk_bf16(float lo, float hi) { unsigned r; asm volatile("v_cvt_pk_bf16_f32 %0, %1, %2" : "=v"(r) : "v"(lo), "v"(hi)); return r; }
;     __device__ __forceinline__ void operator()(const f32x4 (&acc)[2][2][4][2], const Unit& u, int wr, int wc, int fr, int fq) const {
;     ...
;             for (int m = 0; m < 4; ++m) {
;                 const int row = row0 + ai * HALF + m * 16;
;                 const float rs = rsv[ai][m], nrs = rs * -1.44269504089f, rs2 = rs * rs;
;                 typedef float f32x2 __attribute__((ext_vector_type(2)));
;                 float a[8];
; #pragma unroll
;                 for (int n = 0; n < 2; ++n)
; #pragma unroll
;                     for (int hf = 0; hf < 2; ++hf) {
;                         const f32x2 g2 = (f32x2){acc[ai][0][m][n][2 * hf], acc[ai][0][m][n][2 * hf + 1]}, u2 = (f32x2){acc[ai][1][m][n][2 * hf], acc[ai][1][m][n][2 * hf + 1]};
;                         const f32x2 t = g2 * nrs;
;                         f32x2 e; e.x = __builtin_amdgcn_exp2f(t.x); e.y = __builtin_amdgcn_exp2f(t.y);
;                         const f32x2 d = e + 1.0f;
;                         f32x2 r; r.x = __builtin_amdgcn_rcpf(d.x); r.y = __builtin_amdgcn_rcpf(d.y);
;                         const f32x2 o = (g2 * u2) * (r * rs2);
;                         a[n * 4 + 2 * hf] = o.x; a[n * 4 + 2 * hf + 1] = o.y;
;                     }
;                 u32x4 w; w.x = cvt_pk_bf16(a[0], a[1]); w.y = cvt_pk_bf16(a[2], a[3]); w.z = cvt_pk_bf16(a[4], a[5]); w.w = cvt_pk_bf16(a[6], a[7]);
;                 __builtin_nontemporal_store(w, (u32x4*)(O + ((size_t)(u.pm * (ldc >> 6) + (col0 >> 6)) * 256 + (row & 255)) * 64 + (col0 & 63)));
	v_mul_f32_e32 v82, v154, v154
	v_exp_f32_e32 v86, v86
	v_exp_f32_e32 v87, v87
	s_nop 0
	v_pk_add_f32 v[86:87], v[86:87], 1.0 op_sel_hi:[1,0]
	s_nop 0
	v_rcp_f32_e32 v86, v86
	v_rcp_f32_e32 v87, v87
	s_nop 0
	v_pk_mul_f32 v[76:77], v[82:83], v[86:87] op_sel_hi:[0,1]
	v_pk_mul_f32 v[72:73], v[72:73], v[76:77]
	v_pk_mul_f32 v[76:77], v[78:79], v[80:81] op_sel_hi:[1,0]
	s_nop 0
	v_exp_f32_e32 v76, v76
	v_exp_f32_e32 v77, v77
	s_nop 0
	v_pk_add_f32 v[76:77], v[76:77], 1.0 op_sel_hi:[1,0]
	s_nop 0
	v_rcp_f32_e32 v76, v76
	v_rcp_f32_e32 v77, v77
	s_nop 0
	v_pk_mul_f32 v[76:77], v[82:83], v[76:77] op_sel_hi:[0,1]
	v_pk_mul_f32 v[74:75], v[74:75], v[76:77]
	v_pk_mul_f32 v[76:77], v[64:65], v[80:81] op_sel_hi:[1,0]
	v_pk_mul_f32 v[64:65], v[64:65], v[68:69]
	v_exp_f32_e32 v76, v76
	v_exp_f32_e32 v77, v77
	s_nop 0
	v_pk_add_f32 v[76:77], v[76:77], 1.0 op_sel_hi:[1,0]
	s_nop 0
	v_rcp_f32_e32 v76, v76
	v_rcp_f32_e32 v77, v77
	s_nop 0
	v_pk_mul_f32 v[68:69], v[82:83], v[76:77] op_sel_hi:[0,1]
	v_pk_mul_f32 v[68:69], v[64:65], v[68:69]
	v_pk_mul_f32 v[64:65], v[66:67], v[80:81] op_sel_hi:[1,0]
	s_nop 0
	v_exp_f32_e32 v64, v64
	v_exp_f32_e32 v65, v65
	s_nop 0
	v_pk_add_f32 v[64:65], v[64:65], 1.0 op_sel_hi:[1,0]
	s_nop 0
	v_rcp_f32_e32 v64, v64
	v_rcp_f32_e32 v65, v65
	s_nop 0
	v_pk_mul_f32 v[64:65], v[82:83], v[64:65] op_sel_hi:[0,1]
	v_pk_mul_f32 v[70:71], v[70:71], v[64:65]
	v_cvt_pk_bf16_f32 v64, v72, v73
	v_cvt_pk_bf16_f32 v65, v74, v75
	v_cvt_pk_bf16_f32 v66, v68, v69
	s_nop 0
	v_cvt_pk_bf16_f32 v67, v70, v71
	global_store_dwordx4 v[84:85], v[64:67], off offset:2048 nt
	s_nop 1
	v_mul_f32_e32 v64, 0xbfb8aa3b, v143
	v_pk_mul_f32 v[68:69], v[60:61], v[64:65] op_sel_hi:[1,0]
	v_mul_f32_e32 v66, v143, v143
	v_exp_f32_e32 v68, v68
	v_exp_f32_e32 v69, v69
	v_pk_mul_f32 v[50:51], v[50:51], v[64:65] op_sel_hi:[1,0]
	v_mov_b32_e32 v143, v195
	v_exp_f32_e32 v50, v50
	v_pk_add_f32 v[68:69], v[68:69], 1.0 op_sel_hi:[1,0]
	v_exp_f32_e32 v51, v51
	v_rcp_f32_e32 v68, v68
	v_rcp_f32_e32 v69, v69
	v_pk_add_f32 v[50:51], v[50:51], 1.0 op_sel_hi:[1,0]
	s_nop 0
	v_rcp_f32_e32 v50, v50
	v_pk_mul_f32 v[60:61], v[66:67], v[68:69] op_sel_hi:[0,1]
	v_pk_mul_f32 v[56:57], v[56:57], v[60:61]
	v_pk_mul_f32 v[60:61], v[62:63], v[64:65] op_sel_hi:[1,0]
	v_rcp_f32_e32 v51, v51
	v_exp_f32_e32 v60, v60
	v_exp_f32_e32 v61, v61
	v_pk_mul_f32 v[50:51], v[66:67], v[50:51] op_sel_hi:[0,1]
	v_pk_mul_f32 v[54:55], v[54:55], v[50:51]
	v_pk_add_f32 v[60:61], v[60:61], 1.0 op_sel_hi:[1,0]
	v_cvt_pk_bf16_f32 v50, v56, v57
	s_nop 0
	v_rcp_f32_e32 v60, v60
	v_rcp_f32_e32 v61, v61
	s_nop 0
	v_pk_mul_f32 v[60:61], v[66:67], v[60:61] op_sel_hi:[0,1]
	v_pk_mul_f32 v[58:59], v[58:59], v[60:61]
	v_pk_mul_f32 v[60:61], v[48:49], v[64:65] op_sel_hi:[1,0]
	v_pk_mul_f32 v[48:49], v[48:49], v[52:53]
	v_exp_f32_e32 v60, v60
	v_exp_f32_e32 v61, v61
	v_cvt_pk_bf16_f32 v51, v58, v59
	s_nop 0
	v_pk_add_f32 v[60:61], v[60:61], 1.0 op_sel_hi:[1,0]
	s_nop 0
	v_rcp_f32_e32 v60, v60
	v_rcp_f32_e32 v61, v61
	s_nop 0
	v_pk_mul_f32 v[52:53], v[66:67], v[60:61] op_sel_hi:[0,1]
	v_pk_mul_f32 v[48:49], v[48:49], v[52:53]
	s_nop 0
	v_cvt_pk_bf16_f32 v52, v48, v49
	v_lshl_add_u64 v[48:49], s[46:47], 0, v[142:143]
	v_lshl_add_u64 v[48:49], v[48:49], 0, v[140:141]
	v_cvt_pk_bf16_f32 v53, v54, v55
	global_store_dwordx4 v[48:49], v[50:53], off nt
	s_mov_b64 s[46:47], -1
	s_nop 0
	v_mul_f32_e32 v50, 0xbfb8aa3b, v153
	v_pk_mul_f32 v[54:55], v[44:45], v[50:51] op_sel_hi:[1,0]
	v_mul_f32_e32 v52, v153, v153
	v_exp_f32_e32 v54, v54
	v_exp_f32_e32 v55, v55
	s_nop 0
	v_pk_add_f32 v[54:55], v[54:55], 1.0 op_sel_hi:[1,0]
	s_nop 0
	v_rcp_f32_e32 v54, v54
	v_rcp_f32_e32 v55, v55
	s_nop 0
	v_pk_mul_f32 v[44:45], v[52:53], v[54:55] op_sel_hi:[0,1]
	v_pk_mul_f32 v[40:41], v[40:41], v[44:45]
	v_pk_mul_f32 v[44:45], v[46:47], v[50:51] op_sel_hi:[1,0]
	s_nop 0
	v_exp_f32_e32 v44, v44
	v_exp_f32_e32 v45, v45
	s_nop 0
	v_pk_add_f32 v[44:45], v[44:45], 1.0 op_sel_hi:[1,0]
	s_nop 0
	v_rcp_f32_e32 v44, v44
	v_rcp_f32_e32 v45, v45
	s_nop 0
	v_pk_mul_f32 v[44:45], v[52:53], v[44:45] op_sel_hi:[0,1]
	v_pk_mul_f32 v[42:43], v[42:43], v[44:45]
	v_pk_mul_f32 v[44:45], v[32:33], v[50:51] op_sel_hi:[1,0]
	v_pk_mul_f32 v[32:33], v[32:33], v[36:37]
	v_exp_f32_e32 v44, v44
	v_exp_f32_e32 v45, v45
	s_nop 0
; __device__ __forceinline__ unsigned cvt_pk_bf16(float lo, float hi) { unsigned r; asm volatile("v_cvt_pk_bf16_f32 %0, %1, %2" : "=v"(r) : "v"(lo), "v"(hi)); return r; }
; #define PG8_BAR __builtin_amdgcn_s_barrier()
;     __device__ __forceinline__ void operator()(const f32x4 (&acc)[2][2][4][2], const Unit& u, int wr, int wc, int fr, int fq) const {
;     ...
;             for (int m = 0; m < 4; ++m) {
;                 const int row = row0 + ai * HALF + m * 16;
;                 const float rs = rsv[ai][m], nrs = rs * -1.44269504089f, rs2 = rs * rs;
;                 typedef float f32x2 __attribute__((ext_vector_type(2)));
;                 float a[8];
; #pragma unroll
;                 for (int n = 0; n < 2; ++n)
; #pragma unroll
;                     for (int hf = 0; hf < 2; ++hf) {
;                         const f32x2 g2 = (f32x2){acc[ai][0][m][n][2 * hf], acc[ai][0][m][n][2 * hf + 1]}, u2 = (f32x2){acc[ai][1][m][n][2 * hf], acc[ai][1][m][n][2 * hf + 1]};
;                         const f32x2 t = g2 * nrs;
;                         f32x2 e; e.x = __builtin_amdgcn_exp2f(t.x); e.y = __builtin_amdgcn_exp2f(t.y);
;                         const f32x2 d = e + 1.0f;
;                         f32x2 r; r.x = __builtin_amdgcn_rcpf(d.x); r.y = __builtin_amdgcn_rcpf(d.y);
;                         const f32x2 o = (g2 * u2) * (r * rs2);
;                         a[n * 4 + 2 * hf] = o.x; a[n * 4 + 2 * hf + 1] = o.y;
;                     }
;                 u32x4 w; w.x = cvt_pk_bf16(a[0], a[1]); w.y = cvt_pk_bf16(a[2], a[3]); w.z = cvt_pk_bf16(a[4], a[5]); w.w = cvt_pk_bf16(a[6], a[7]);
;                 __builtin_nontemporal_store(w, (u32x4*)(O + ((size_t)(u.pm * (ldc >> 6) + (col0 >> 6)) * 256 + (row & 255)) * 64 + (col0 & 63)));
; template <class Epi, class Sched, bool ALIGN_EPI = false, bool SP2 = true>
; __device__ __forceinline__ void gemm_phase(PG8_LAS unsigned char* lds, const Gemm g, const Sched& S, const Epi& E) {
;     ...
;         if (!has_next) break;
; #pragma unroll
;         for (int a = 0; a < 2; ++a)
; #pragma unroll
;             for (int b = 0; b < 2; ++b)
; #pragma unroll
;                 for (int m = 0; m < 4; ++m)
; #pragma unroll
;                     for (int n = 0; n < 2; ++n) acc[a][b][m][n] = (f32x4){0.f, 0.f, 0.f, 0.f};
;         cur = nxt; cA = nA; cB = nB; ++ui;
;         if constexpr (ALIGN_EPI) { if (wr == 1) PG8_BAR; }
	v_pk_add_f32 v[44:45], v[44:45], 1.0 op_sel_hi:[1,0]
	s_nop 0
	v_rcp_f32_e32 v44, v44
	v_rcp_f32_e32 v45, v45
	s_nop 0
	v_pk_mul_f32 v[36:37], v[52:53], v[44:45] op_sel_hi:[0,1]
	v_pk_mul_f32 v[36:37], v[32:33], v[36:37]
	v_pk_mul_f32 v[32:33], v[34:35], v[50:51] op_sel_hi:[1,0]
	s_nop 0
	v_exp_f32_e32 v32, v32
	v_exp_f32_e32 v33, v33
	s_nop 0
	v_pk_add_f32 v[32:33], v[32:33], 1.0 op_sel_hi:[1,0]
	s_nop 0
	v_rcp_f32_e32 v32, v32
	v_rcp_f32_e32 v33, v33
	s_nop 0
	v_pk_mul_f32 v[32:33], v[52:53], v[32:33] op_sel_hi:[0,1]
	v_pk_mul_f32 v[38:39], v[38:39], v[32:33]
	v_cvt_pk_bf16_f32 v32, v40, v41
	v_cvt_pk_bf16_f32 v33, v42, v43
	v_cvt_pk_bf16_f32 v34, v36, v37
	s_nop 0
	v_cvt_pk_bf16_f32 v35, v38, v39
	global_store_dwordx4 v[48:49], v[32:35], off offset:2048 nt
	s_nop 1
	v_mul_f32_e32 v32, 0xbfb8aa3b, v152
	v_pk_mul_f32 v[36:37], v[28:29], v[32:33] op_sel_hi:[1,0]
	v_mul_f32_e32 v34, v152, v152
	v_exp_f32_e32 v36, v36
	v_exp_f32_e32 v37, v37
	s_nop 0
	v_pk_add_f32 v[36:37], v[36:37], 1.0 op_sel_hi:[1,0]
	s_nop 0
	v_rcp_f32_e32 v36, v36
	v_rcp_f32_e32 v37, v37
	s_nop 0
	v_pk_mul_f32 v[28:29], v[34:35], v[36:37] op_sel_hi:[0,1]
	v_pk_mul_f32 v[24:25], v[24:25], v[28:29]
	v_pk_mul_f32 v[28:29], v[30:31], v[32:33] op_sel_hi:[1,0]
	s_nop 0
	v_exp_f32_e32 v28, v28
	v_exp_f32_e32 v29, v29
	s_nop 0
	v_pk_add_f32 v[28:29], v[28:29], 1.0 op_sel_hi:[1,0]
	s_nop 0
	v_rcp_f32_e32 v28, v28
	v_rcp_f32_e32 v29, v29
	s_nop 0
	v_pk_mul_f32 v[28:29], v[34:35], v[28:29] op_sel_hi:[0,1]
	v_pk_mul_f32 v[26:27], v[26:27], v[28:29]
	v_pk_mul_f32 v[28:29], v[16:17], v[32:33] op_sel_hi:[1,0]
	v_pk_mul_f32 v[16:17], v[16:17], v[20:21]
	v_exp_f32_e32 v28, v28
	v_exp_f32_e32 v29, v29
	s_nop 0
	v_pk_add_f32 v[28:29], v[28:29], 1.0 op_sel_hi:[1,0]
	s_nop 0
	v_rcp_f32_e32 v28, v28
	v_rcp_f32_e32 v29, v29
	s_nop 0
	v_pk_mul_f32 v[20:21], v[34:35], v[28:29] op_sel_hi:[0,1]
	v_pk_mul_f32 v[20:21], v[16:17], v[20:21]
	v_pk_mul_f32 v[16:17], v[18:19], v[32:33] op_sel_hi:[1,0]
	s_nop 0
	v_exp_f32_e32 v16, v16
	v_exp_f32_e32 v17, v17
	s_nop 0
	v_pk_add_f32 v[16:17], v[16:17], 1.0 op_sel_hi:[1,0]
	s_nop 0
	v_rcp_f32_e32 v16, v16
	v_rcp_f32_e32 v17, v17
	s_nop 0
	v_pk_mul_f32 v[16:17], v[34:35], v[16:17] op_sel_hi:[0,1]
	v_pk_mul_f32 v[22:23], v[22:23], v[16:17]
	v_cvt_pk_bf16_f32 v16, v24, v25
	v_cvt_pk_bf16_f32 v17, v26, v27
	v_cvt_pk_bf16_f32 v18, v20, v21
	v_add_co_u32_e32 v20, vcc, s23, v48
	v_cvt_pk_bf16_f32 v19, v22, v23
	s_nop 1
	v_addc_co_u32_e32 v21, vcc, 0, v49, vcc
	global_store_dwordx4 v[20:21], v[16:19], off nt
	s_andn2_b64 vcc, exec, s[36:37]
	s_nop 0
	v_mul_f32_e32 v16, 0xbfb8aa3b, v151
	v_pk_mul_f32 v[22:23], v[12:13], v[16:17] op_sel_hi:[1,0]
	v_mul_f32_e32 v18, v151, v151
	v_exp_f32_e32 v22, v22
	v_exp_f32_e32 v23, v23
	s_nop 0
	v_pk_add_f32 v[22:23], v[22:23], 1.0 op_sel_hi:[1,0]
	s_nop 0
	v_rcp_f32_e32 v22, v22
	v_rcp_f32_e32 v23, v23
	s_nop 0
	v_pk_mul_f32 v[12:13], v[18:19], v[22:23] op_sel_hi:[0,1]
	v_pk_mul_f32 v[8:9], v[8:9], v[12:13]
	v_pk_mul_f32 v[12:13], v[14:15], v[16:17] op_sel_hi:[1,0]
	s_nop 0
	v_exp_f32_e32 v12, v12
	v_exp_f32_e32 v13, v13
	s_nop 0
	v_pk_add_f32 v[12:13], v[12:13], 1.0 op_sel_hi:[1,0]
	s_nop 0
	v_rcp_f32_e32 v12, v12
	v_rcp_f32_e32 v13, v13
	s_nop 0
	v_pk_mul_f32 v[12:13], v[18:19], v[12:13] op_sel_hi:[0,1]
	v_pk_mul_f32 v[10:11], v[10:11], v[12:13]
	v_pk_mul_f32 v[12:13], v[4:5], v[16:17] op_sel_hi:[1,0]
	s_nop 0
	v_exp_f32_e32 v12, v12
	v_exp_f32_e32 v13, v13
	s_nop 0
	v_pk_add_f32 v[12:13], v[12:13], 1.0 op_sel_hi:[1,0]
	s_nop 0
	v_rcp_f32_e32 v12, v12
	v_rcp_f32_e32 v13, v13
	s_nop 0
	v_pk_mul_f32 v[4:5], v[18:19], v[12:13] op_sel_hi:[0,1]
	v_pk_mul_f32 v[4:5], v[0:1], v[4:5]
	v_pk_mul_f32 v[0:1], v[6:7], v[16:17] op_sel_hi:[1,0]
	s_nop 0
	v_exp_f32_e32 v0, v0
	v_exp_f32_e32 v1, v1
	s_nop 0
	v_pk_add_f32 v[0:1], v[0:1], 1.0 op_sel_hi:[1,0]
	s_nop 0
	v_rcp_f32_e32 v0, v0
	v_rcp_f32_e32 v1, v1
	s_nop 0
	v_pk_mul_f32 v[0:1], v[18:19], v[0:1] op_sel_hi:[0,1]
	v_pk_mul_f32 v[6:7], v[2:3], v[0:1]
	v_cvt_pk_bf16_f32 v0, v8, v9
	v_cvt_pk_bf16_f32 v1, v10, v11
	v_cvt_pk_bf16_f32 v2, v4, v5
	s_nop 0
	v_cvt_pk_bf16_f32 v3, v6, v7
	global_store_dwordx4 v[20:21], v[0:3], off offset:2048 nt
	s_cbranch_vccnz .LBB0_124
	s_andn2_b64 vcc, exec, s[0:1]
	s_cbranch_vccnz .LBB0_123
	s_barrier
	s_branch .LBB0_123
